# baseline (speedup 1.0000x reference)
; __global__ void __launch_bounds__(256, 2) fwd_kernel(Params p) {
;     ...
;             } else if (sp == 6) {
;                 for (int tile = bid; tile < MT * 22; tile += nb) {
;                     int mt, nt;
;                     if (tile < 128 * 22) { const int x = tile & 7, q = tile >> 3, g = q >> 6, r = q & 63; mt = (r & 15) * 8 + x; nt = g * 4 + (r >> 4); } else { mt = 128; nt = tile - 128 * 22; }
;                     ffn1_big(pq, l, mt, nt, smem);
.LBB0_29:
	s_and_b64 vcc, exec, s[4:5]
	s_cbranch_vccz .LBB0_39
	s_cmpk_gt_i32 s78, 0xb15
	s_cbranch_scc1 .LBB0_39
	s_cmpk_lt_i32 s78, 0x116
	s_cbranch_scc1 .Lstag_ffn1
	s_sleep 127
	s_sleep 127
	s_sleep 127
	s_sleep 127
	s_sleep 127
	s_sleep 127
